# gate and index phases: one static s_setprio 1 for waves 4-7 (reset at the common phase end)
# baseline (speedup 1.0000x reference)
.LBB0_97:
	s_andn2_b64 vcc, exec, s[0:1]
	s_cbranch_vccnz .LBB0_109
	s_cmp_lg_u32 s70, 2
	s_cbranch_scc1 .LBB0_109
	v_mov_b32_e32 v33, v165
	s_cmpk_gt_i32 s10, 0x1ff
	v_readfirstlane_b32 s24, v33
	s_cbranch_scc1 .LBB0_109
	s_mov_b32 s55, s15
	s_mov_b64 s[50:51], s[6:7]
	s_mov_b64 s[48:49], s[16:17]
	s_mov_b64 s[44:45], s[8:9]
	s_mov_b64 s[26:27], s[12:13]
	s_mov_b64 s[28:29], s[18:19]
	v_readlane_b32 s4, v251, 52
	v_readlane_b32 s0, v253, 7
	v_readlane_b32 s5, v251, 53
	v_readlane_b32 s6, v251, 54
	v_readlane_b32 s7, v251, 55
	v_readlane_b32 s8, v251, 56
	v_readlane_b32 s9, v251, 57
	v_readlane_b32 s10, v251, 58
	v_readlane_b32 s11, v251, 59
	v_readlane_b32 s12, v251, 60
	v_readlane_b32 s13, v251, 61
	v_readlane_b32 s14, v251, 62
	v_readlane_b32 s15, v251, 63
	v_readlane_b32 s0, v253, 13
	s_add_u32 s22, s78, 0x2c300000
	v_readlane_b32 s16, v252, 0
	v_readlane_b32 s17, v252, 1
	v_readlane_b32 s18, v252, 2
	v_readlane_b32 s19, v252, 3
	s_mov_b64 s[4:5], s[8:9]
	s_addc_u32 s30, s79, 0
	s_lshl_b64 s[0:1], s[96:97], 16
	s_mov_b64 s[6:7], s[10:11]
	s_mov_b64 s[8:9], s[12:13]
	s_mov_b64 s[10:11], s[14:15]
	s_add_u32 s0, s10, s0
	s_mov_b64 s[12:13], s[16:17]
	s_addc_u32 s1, s11, s1
	s_lshl_b64 s[2:3], s[96:97], 12
	s_add_u32 s2, s12, s2
	s_addc_u32 s3, s13, s3
	s_mov_b64 s[14:15], s[18:19]
	s_mov_b64 s[18:19], s[28:29]
	s_add_u32 s28, s78, s41
	s_addc_u32 s29, s79, s40
	s_lshl_b32 s24, s24, 2
	s_and_b32 s24, s24, 0xffffff00
	s_waitcnt vmcnt(0)
	v_and_b32_e32 v44, 15, v33
	s_ashr_i32 s25, s24, 31
	s_mov_b64 s[12:13], s[26:27]
	s_lshl_b64 s[34:35], s[24:25], 1
	v_lshlrev_b32_e32 v2, 12, v44
	v_mov_b32_e32 v3, v32
	s_add_u32 s36, s12, s34
	v_lshl_add_u64 v[2:3], s[28:29], 0, v[2:3]
	s_addc_u32 s37, s13, s35
	v_and_b32_e32 v0, 48, v33
	v_mov_b32_e32 v1, v32
	v_lshl_add_u64 v[2:3], v[2:3], 0, s[34:35]
	v_lshl_add_u64 v[4:5], s[36:37], 0, v[0:1]
	v_lshl_add_u64 v[0:1], v[2:3], 0, v[0:1]
	s_mov_b64 s[28:29], 0x1100000
	v_lshl_add_u64 v[6:7], v[0:1], 0, s[28:29]
	v_and_or_b32 v0, v33, 63, s24
	v_lshrrev_b32_e32 v1, 2, v33
	v_lshlrev_b32_e32 v2, 4, v0
	v_ashrrev_i32_e32 v0, 2, v33
	v_and_b32_e32 v1, 12, v1
	v_and_or_b32 v0, v0, -16, v1
	s_movk_i32 s4, 0x100
	v_ashrrev_i32_e32 v1, 31, v0
	v_readlane_b32 s10, v253, 6
	v_cmp_gt_i32_e64 s[36:37], s4, v33
	v_lshlrev_b32_e32 v3, 4, v33
	v_lshl_add_u64 v[8:9], v[0:1], 2, s[18:19]
	v_lshl_add_u32 v1, v44, 2, 0
	v_lshlrev_b32_e32 v0, 6, v0
	v_readlane_b32 s4, v253, 3
	s_lshl_b32 s31, s10, 9
	s_lshl_b32 s34, s4, 9
	s_lshl_b32 s35, s10, 5
	s_lshl_b32 s40, s4, 5
	v_add_u32_e32 v45, 0, v2
	v_add_u32_e32 v46, 0, v3
	v_add_u32_e32 v47, v1, v0
	s_mov_b32 s41, s10
.LBB0_101:
	v_readfirstlane_b32 s98, v165
	s_lshr_b32 s98, s98, 8
	s_cmp_eq_u32 s98, 1
	s_cbranch_scc0 .Lgate_noprio
	s_setprio 1
.Lgate_noprio:
	s_ashr_i32 s38, s41, 1
	s_lshl_b32 s24, s41, 5
	s_lshl_b32 s25, s38, 6
	s_and_b32 s39, s25, 0xfc0
	s_and_b32 s24, s24, 0xfffff000
	s_or_b32 s28, s39, s24
	v_or_b32_e32 v0, s28, v44
	v_ashrrev_i32_e32 v1, 31, v0
	v_lshlrev_b64 v[0:1], 12, v[0:1]
	s_barrier
	v_lshl_add_u64 v[12:13], v[4:5], 0, v[0:1]
	s_mov_b32 s4, 0x10000
	s_mov_b32 s24, 0x30000
	v_add_co_u32_e32 v0, vcc, 0x10000, v12
	s_nop 1
	v_addc_co_u32_e32 v1, vcc, 0, v13, vcc
	v_add_co_u32_e32 v2, vcc, 0x20000, v12
	s_nop 1
	v_addc_co_u32_e32 v3, vcc, 0, v13, vcc
	v_add_co_u32_e32 v10, vcc, 0x30000, v12
	s_nop 1
	v_addc_co_u32_e32 v11, vcc, 0, v13, vcc
	global_load_dwordx4 v[192:195], v[6:7], off
	global_load_dwordx4 v[76:79], v[12:13], off
	global_load_dwordx4 v[80:83], v[0:1], off
	global_load_dwordx4 v[84:87], v[2:3], off
	global_load_dwordx4 v[88:91], v[10:11], off
	global_load_dwordx4 v[196:199], v[6:7], off offset:64
	global_load_dwordx4 v[92:95], v[12:13], off offset:64
	global_load_dwordx4 v[96:99], v[0:1], off offset:64
	global_load_dwordx4 v[100:103], v[2:3], off offset:64
	global_load_dwordx4 v[104:107], v[10:11], off offset:64
	global_load_dwordx4 v[200:203], v[6:7], off offset:128
	global_load_dwordx4 v[108:111], v[12:13], off offset:128
	global_load_dwordx4 v[112:115], v[0:1], off offset:128
	global_load_dwordx4 v[116:119], v[2:3], off offset:128
	global_load_dwordx4 v[120:123], v[10:11], off offset:128
	global_load_dwordx4 v[204:207], v[6:7], off offset:192
	global_load_dwordx4 v[124:127], v[12:13], off offset:192
	global_load_dwordx4 v[128:131], v[0:1], off offset:192
	global_load_dwordx4 v[132:135], v[2:3], off offset:192
	global_load_dwordx4 v[136:139], v[10:11], off offset:192
	global_load_dwordx4 v[208:211], v[6:7], off offset:256
	global_load_dwordx4 v[140:143], v[12:13], off offset:256
	global_load_dwordx4 v[144:147], v[0:1], off offset:256
	global_load_dwordx4 v[148:151], v[2:3], off offset:256
	global_load_dwordx4 v[152:155], v[10:11], off offset:256
	global_load_dwordx4 v[212:215], v[6:7], off offset:320
	global_load_dwordx4 v[156:159], v[12:13], off offset:320
	global_load_dwordx4 v[160:163], v[0:1], off offset:320
	global_load_dwordx4 v[224:227], v[2:3], off offset:320
	global_load_dwordx4 v[228:231], v[10:11], off offset:320
	global_load_dwordx4 v[216:219], v[6:7], off offset:384
	global_load_dwordx4 v[232:235], v[12:13], off offset:384
	global_load_dwordx4 v[236:239], v[0:1], off offset:384
	global_load_dwordx4 v[240:243], v[2:3], off offset:384
	global_load_dwordx4 v[244:247], v[10:11], off offset:384
	global_load_dwordx4 v[220:223], v[6:7], off offset:448
	global_load_dwordx4 v[40:43], v[12:13], off offset:448
	global_load_dwordx4 v[48:51], v[0:1], off offset:448
	global_load_dwordx4 v[52:55], v[2:3], off offset:448
	global_load_dwordx4 v[56:59], v[10:11], off offset:448
	s_waitcnt vmcnt(35)
	v_mfma_f32_16x16x32_bf16 v[18:21], v[76:79], v[192:195], 0
	v_mfma_f32_16x16x32_bf16 v[22:25], v[80:83], v[192:195], 0
	v_mfma_f32_16x16x32_bf16 v[26:29], v[84:87], v[192:195], 0
	v_mfma_f32_16x16x32_bf16 v[14:17], v[88:91], v[192:195], 0
	s_waitcnt vmcnt(30)
	v_mfma_f32_16x16x32_bf16 v[18:21], v[92:95], v[196:199], v[18:21]
	v_mfma_f32_16x16x32_bf16 v[22:25], v[96:99], v[196:199], v[22:25]
	v_mfma_f32_16x16x32_bf16 v[26:29], v[100:103], v[196:199], v[26:29]
	v_mfma_f32_16x16x32_bf16 v[14:17], v[104:107], v[196:199], v[14:17]
	s_waitcnt vmcnt(25)
	v_mfma_f32_16x16x32_bf16 v[18:21], v[108:111], v[200:203], v[18:21]
	v_mfma_f32_16x16x32_bf16 v[22:25], v[112:115], v[200:203], v[22:25]
	v_mfma_f32_16x16x32_bf16 v[26:29], v[116:119], v[200:203], v[26:29]
	v_mfma_f32_16x16x32_bf16 v[14:17], v[120:123], v[200:203], v[14:17]
	s_waitcnt vmcnt(20)
	v_mfma_f32_16x16x32_bf16 v[18:21], v[124:127], v[204:207], v[18:21]
	v_mfma_f32_16x16x32_bf16 v[22:25], v[128:131], v[204:207], v[22:25]
	v_mfma_f32_16x16x32_bf16 v[26:29], v[132:135], v[204:207], v[26:29]
	v_mfma_f32_16x16x32_bf16 v[14:17], v[136:139], v[204:207], v[14:17]
	s_waitcnt vmcnt(15)
	v_mfma_f32_16x16x32_bf16 v[18:21], v[140:143], v[208:211], v[18:21]
	v_mfma_f32_16x16x32_bf16 v[22:25], v[144:147], v[208:211], v[22:25]
	v_mfma_f32_16x16x32_bf16 v[26:29], v[148:151], v[208:211], v[26:29]
	v_mfma_f32_16x16x32_bf16 v[14:17], v[152:155], v[208:211], v[14:17]
	s_waitcnt vmcnt(10)
	v_mfma_f32_16x16x32_bf16 v[18:21], v[156:159], v[212:215], v[18:21]
	v_mfma_f32_16x16x32_bf16 v[22:25], v[160:163], v[212:215], v[22:25]
	v_mfma_f32_16x16x32_bf16 v[26:29], v[224:227], v[212:215], v[26:29]
	v_mfma_f32_16x16x32_bf16 v[14:17], v[228:231], v[212:215], v[14:17]
	s_waitcnt vmcnt(5)
	v_mfma_f32_16x16x32_bf16 v[18:21], v[232:235], v[216:219], v[18:21]
	v_mfma_f32_16x16x32_bf16 v[22:25], v[236:239], v[216:219], v[22:25]
	v_mfma_f32_16x16x32_bf16 v[26:29], v[240:243], v[216:219], v[26:29]
	v_mfma_f32_16x16x32_bf16 v[14:17], v[244:247], v[216:219], v[14:17]
	s_waitcnt vmcnt(0)
	v_mfma_f32_16x16x32_bf16 v[18:21], v[40:43], v[220:223], v[18:21]
	v_mfma_f32_16x16x32_bf16 v[22:25], v[48:51], v[220:223], v[22:25]
	v_mfma_f32_16x16x32_bf16 v[26:29], v[52:55], v[220:223], v[26:29]
	v_mfma_f32_16x16x32_bf16 v[14:17], v[56:59], v[220:223], v[14:17]
	s_nop 7
	ds_write_b128 v45, v[18:21]
	ds_write_b128 v45, v[22:25] offset:1024
	ds_write_b128 v45, v[26:29] offset:2048
	ds_write_b128 v45, v[14:17] offset:3072
	s_waitcnt lgkmcnt(0)
	s_barrier
	s_and_saveexec_b64 s[24:25], s[36:37]
	s_cbranch_execz .LBB0_103
	ds_read_b128 v[0:3], v46
	ds_read_b128 v[10:13], v46 offset:4096
	s_ashr_i32 s29, s28, 31
	s_waitcnt lgkmcnt(0)
	v_pk_add_f32 v[12:13], v[2:3], v[12:13]
	v_pk_add_f32 v[10:11], v[0:1], v[10:11]
	ds_read_b128 v[0:3], v46 offset:8192
	s_waitcnt lgkmcnt(0)
	v_pk_add_f32 v[12:13], v[12:13], v[2:3]
	v_pk_add_f32 v[10:11], v[10:11], v[0:1]
	ds_read_b128 v[0:3], v46 offset:12288
	s_waitcnt lgkmcnt(0)
	v_pk_add_f32 v[12:13], v[12:13], v[2:3]
	v_pk_add_f32 v[10:11], v[10:11], v[0:1]
	ds_read_b128 v[0:3], v46 offset:16384
	s_waitcnt lgkmcnt(0)
	v_pk_add_f32 v[12:13], v[12:13], v[2:3]
	v_pk_add_f32 v[10:11], v[10:11], v[0:1]
	ds_read_b128 v[0:3], v46 offset:20480
	s_waitcnt lgkmcnt(0)
	v_pk_add_f32 v[12:13], v[12:13], v[2:3]
	v_pk_add_f32 v[10:11], v[10:11], v[0:1]
	ds_read_b128 v[0:3], v46 offset:24576
	s_waitcnt lgkmcnt(0)
	v_pk_add_f32 v[12:13], v[12:13], v[2:3]
	v_pk_add_f32 v[10:11], v[10:11], v[0:1]
	ds_read_b128 v[0:3], v46 offset:28672
	s_waitcnt lgkmcnt(0)
	v_pk_add_f32 v[10:11], v[10:11], v[0:1]
	v_lshl_add_u64 v[0:1], s[28:29], 2, v[8:9]
	v_pk_add_f32 v[12:13], v[12:13], v[2:3]
	global_load_dwordx4 v[0:3], v[0:1], off
	s_waitcnt vmcnt(0)
	v_mul_f32_e32 v0, v10, v0
	v_mul_f32_e32 v1, v11, v1
	v_add_u32_e32 v10, 0x8000, v47
	ds_write2_b32 v10, v0, v1 offset1:16
	v_mul_f32_e32 v0, v12, v2
	v_mul_f32_e32 v1, v13, v3
	ds_write2_b32 v10, v0, v1 offset0:32 offset1:48

.LBB0_144:
	s_or_b64 exec, exec, s[24:25]
	s_add_i32 s82, s82, 1
	v_readlane_b32 s0, v253, 3
	s_mul_i32 s0, s82, s0
	s_add_i32 s24, s0, s10
	s_cmpk_gt_i32 s24, 0x7ff
	s_waitcnt vmcnt(63) expcnt(7) lgkmcnt(15)
	s_barrier
	s_cbranch_scc1 .LBB0_802
.LBB0_145:
	v_readfirstlane_b32 s98, v165
	s_lshr_b32 s98, s98, 8
	s_cmp_eq_u32 s98, 1
	s_cbranch_scc0 .Lidx_noprio
	s_setprio 1
.Lidx_noprio:
	v_readlane_b32 s2, v253, 42
	v_readlane_b32 s3, v253, 43
	s_mov_b64 s[0:1], -1
	s_and_b64 vcc, exec, s[2:3]
	s_cbranch_vccz .LBB0_147
	s_ashr_i32 s3, s24, 9
	s_and_b32 s2, s24, 0x1ff
	s_mov_b64 s[0:1], 0

.LBB0_2452:
	s_setprio 0
	s_add_i32 s22, s58, 1
	s_cmp_ge_i32 s22, s59
	s_cbranch_scc0 .LBB0_2453
	s_getpc_b64 s[98:99]
